# v010 plus: differential attention runs the softmax(0) row-sum tree in the gaps of PV(1)'s bare MFMAs instead of behind them
# speedup vs baseline: 1.0064x; 1.0064x over previous
.LBB0_396:
	s_waitcnt lgkmcnt(0)
	v_mfma_f32_32x32x16_bf16 v[64:79], v[94:97], v[6:9], v[64:79]
	v_add_f32_e32 v129, v206, v207
	v_add_f32_e32 v130, v208, v209
	ds_read_b64_tr_b16 v[98:99], v204 offset:16896
	ds_read_b64_tr_b16 v[100:101], v204 offset:18944
	ds_read_b64_tr_b16 v[112:113], v204 offset:20992
	ds_read_b64_tr_b16 v[114:115], v204 offset:23040
	ds_read_b64_tr_b16 v[94:95], v204 offset:24576
	ds_read_b64_tr_b16 v[96:97], v204 offset:26624
	ds_read_b64_tr_b16 v[118:119], v204 offset:27136
	ds_read_b64_tr_b16 v[116:117], v204 offset:25088
	ds_read_b64_tr_b16 v[120:121], v204 offset:28672
	ds_read_b64_tr_b16 v[122:123], v204 offset:30720
	ds_read_b64_tr_b16 v[126:127], v204 offset:31232
	ds_read_b64_tr_b16 v[124:125], v204 offset:29184
	v_mfma_f32_32x32x16_bf16 v[64:79], v[90:93], v[2:5], v[64:79]
	v_add_f32_e32 v129, v129, v130
	v_add_f32_e32 v130, v104, v105
	s_waitcnt lgkmcnt(0)
	v_mfma_f32_32x32x16_bf16 v[64:79], v[94:97], v[10:13], v[64:79]
	v_add_f32_e32 v131, v106, v107
	v_add_f32_e32 v130, v130, v131
	ds_read_b64_tr_b16 v[88:89], v204 offset:17408
	ds_read_b64_tr_b16 v[90:91], v204 offset:19456
	ds_read_b64_tr_b16 v[92:93], v204 offset:21504
	ds_read_b64_tr_b16 v[94:95], v204 offset:23552
	v_mfma_f32_32x32x16_bf16 v[64:79], v[120:123], v[84:87], v[64:79]
	v_add_f32_e32 v131, v108, v109
	v_add_f32_e32 v132, v110, v111
	v_mfma_f32_32x32x16_bf16 v[48:63], v[98:101], v[6:9], v[48:63]
	v_add_f32_e32 v128, v196, v205
	v_add_f32_e32 v131, v131, v132
	ds_read_b64_tr_b16 v[96:97], v204 offset:25600
	ds_read_b64_tr_b16 v[98:99], v204 offset:27648
	ds_read_b64_tr_b16 v[100:101], v204 offset:29696
	ds_read_b64_tr_b16 v[102:103], v204 offset:31744
	v_mfma_f32_32x32x16_bf16 v[48:63], v[112:115], v[2:5], v[48:63]
	v_add_f32_e32 v132, v15, v182
	v_add_f32_e32 v128, v132, v128
	v_mfma_f32_32x32x16_bf16 v[48:63], v[116:119], v[10:13], v[48:63]
	v_add_f32_e32 v128, v128, v129
	v_add_f32_e32 v128, v130, v128
	ds_read_b64_tr_b16 v[112:113], v204 offset:17920
	ds_read_b64_tr_b16 v[114:115], v204 offset:19968
	ds_read_b64_tr_b16 v[116:117], v204 offset:22016
	ds_read_b64_tr_b16 v[118:119], v204 offset:24064
	v_mfma_f32_32x32x16_bf16 v[48:63], v[124:127], v[84:87], v[48:63]
	v_add_f32_e32 v129, v210, v211
	v_add_f32_e32 v130, v212, v213
	s_waitcnt lgkmcnt(0)
	v_mfma_f32_32x32x16_bf16 v[32:47], v[88:91], v[6:9], v[32:47]
	v_add_f32_e32 v128, v131, v128
	v_add_f32_e32 v129, v129, v130
	ds_read_b64_tr_b16 v[88:89], v204 offset:26112
	ds_read_b64_tr_b16 v[90:91], v204 offset:28160
	ds_read_b64_tr_b16 v[120:121], v204 offset:30208
	ds_read_b64_tr_b16 v[122:123], v204 offset:32256
	v_mfma_f32_32x32x16_bf16 v[32:47], v[92:95], v[2:5], v[32:47]
	v_add_f32_e32 v130, v214, v215
	v_add_f32_e32 v131, v216, v218
	v_mfma_f32_32x32x16_bf16 v[32:47], v[96:99], v[10:13], v[32:47]
	v_add_f32_e32 v130, v130, v131
	v_add_f32_e32 v129, v129, v130
	v_mfma_f32_32x32x16_bf16 v[32:47], v[100:103], v[84:87], v[32:47]
	v_add_f32_e32 v130, v217, v219
	v_add_f32_e32 v131, v220, v222
	v_mfma_f32_32x32x16_bf16 v[16:31], v[112:115], v[6:9], v[16:31]
	v_add_f32_e32 v130, v130, v131
	v_add_f32_e32 v129, v130, v129
	v_mfma_f32_32x32x16_bf16 v[16:31], v[116:119], v[2:5], v[16:31]
	v_add_f32_e32 v130, v221, v223
	v_add_f32_e32 v131, v232, v233
	s_waitcnt lgkmcnt(0)
	v_mfma_f32_32x32x16_bf16 v[16:31], v[88:91], v[10:13], v[16:31]
	v_add_f32_e32 v130, v130, v131
	v_add_f32_e32 v129, v130, v129
	v_mfma_f32_32x32x16_bf16 v[16:31], v[120:123], v[84:87], v[16:31]
	v_add_f32_e32 v128, v128, v129
	v_fmac_f32_e32 v128, v203, v0
	v_fmac_f32_e32 v80, v128, v14
	s_setprio 0
	s_and_b64 vcc, exec, s[38:39]
	s_cbranch_vccnz .LBB0_398
	s_xor_b32 s12, s14, 0x8000
	v_add_u32_e32 v2, s12, v191
	s_waitcnt vmcnt(0)
	ds_write_b128 v2, v[160:163]
	ds_write_b128 v2, v[164:167] offset:8192
	ds_write_b128 v2, v[168:171] offset:16384
	ds_write_b128 v2, v[172:175] offset:24576
.LBB0_398:
	s_xor_b32 s48, s48, 1
	s_add_u32 s18, s18, 0x10000
	s_addc_u32 s19, s19, 0
	s_addk_i32 s50, 0x80
	s_add_i32 s51, s51, 1
	s_cmp_eq_u32 s6, s18
	v_add_u32_e32 v202, 0xffffff80, v202
	s_waitcnt lgkmcnt(0)
	s_barrier
	s_cbranch_scc1 .LBB0_400
	v_mov_b32_e32 v203, v80
	s_cmp_lt_u32 s51, s46
	s_cselect_b64 s[12:13], -1, 0
	s_cmp_ge_u32 s51, s46
	s_cbranch_scc0 .LBB0_376
	s_branch .LBB0_377
